# speedup vs baseline: 1.0505x; 1.0033x over previous
; #define AT_WRITE(BUF, KR, VR, CR) do { char* _b = sm + (BUF) * BUFSZ; *(bf16x8*)(_b + soff) = KR; *(bf16x8*)(_b + 64 * KP + soff) = VR; \
;     if (cth) *(float*)(_b + 128 * KP + tid * 4) = -(CR) * LOG2E; } while (0)
; __device__ __forceinline__ void attn_item(const int WV, const Params& P, int bh, int qb) {
;     ...
;   AT_WRITE(0, kA, vA, cA);
;   AT_WRITE(1, kB, vB, cB);
.LBB0_375:
	s_or_b64 exec, exec, s[20:21]
	s_movk_i32 s13, 0x90
	v_mul_lo_u32 v19, v18, s13
	v_lshl_add_u32 v126, v25, 4, v19
	s_waitcnt vmcnt(3)
	ds_write_b128 v126, v[2:5]
	s_waitcnt vmcnt(2)
	v_and_b32_e32 v175, 1, v162
	v_lshlrev_b32_e32 v175, 3, v175
	v_sub_u32_e32 v175, v126, v175
	v_add_u32_e32 v175, 0x2400, v175
	ds_write2_b64 v175, v[6:7], v[8:9] offset1:2
	s_and_saveexec_b64 s[20:21], s[4:5]
	s_xor_b64 s[20:21], exec, s[20:21]
	s_cbranch_execz .LBB0_377
	s_waitcnt vmcnt(1)
	ds_write_b128 v126, v[10:13] offset:18688
	s_waitcnt vmcnt(0)
	v_and_b32_e32 v175, 1, v162
	v_lshlrev_b32_e32 v175, 3, v175
	v_sub_u32_e32 v175, v126, v175
	v_add_u32_e32 v175, 0x6d00, v175
	ds_write2_b64 v175, v[14:15], v[16:17] offset1:2
.LBB0_377:
	s_or_saveexec_b64 s[20:21], s[20:21]
	v_lshlrev_b32_e32 v127, 2, v112
	s_xor_b64 exec, exec, s[20:21]
	s_cbranch_execz .LBB0_379
	v_mul_f32_e32 v2, 0xbfb8aa3b, v119
	ds_write_b32 v127, v2 offset:18432
	s_waitcnt vmcnt(1)
	ds_write_b128 v126, v[10:13] offset:18688
	s_waitcnt vmcnt(0)
	v_and_b32_e32 v175, 1, v162
	v_lshlrev_b32_e32 v175, 3, v175
	v_sub_u32_e32 v175, v126, v175
	v_add_u32_e32 v175, 0x6d00, v175
	ds_write2_b64 v175, v[14:15], v[16:17] offset1:2
	v_mul_f32_e32 v2, 0xbfb8aa3b, v117
	ds_write_b32 v127, v2 offset:37120

; __device__ __forceinline__ void attn_item(const int WV, const Params& P, int bh, int qb) {
;     ...
;       float mx = -INFINITY;
; #pragma unroll
;       for (int kb = 0; kb < 2; ++kb)
; #pragma unroll
;         for (int i = 0; i < 16; ++i) mx = fmaxf(mx, st[kb][i]);
;       {
;         auto rr = __builtin_amdgcn_permlane32_swap(__float_as_uint(mx), __float_as_uint(mx), false, false);
;         mx = fmaxf(__uint_as_float(rr[0]), __uint_as_float(rr[1]));
;       }
;       const float mn = fmaxf(m, mx);
;       const float alpha = __builtin_amdgcn_exp2f(m - mn);
;       m = mn;
;       float ps = 0.f;
;       bf16x8 pb[4];
; #pragma unroll
;       for (int kb = 0; kb < 2; ++kb)
; #pragma unroll
;         for (int i = 0; i < 16; i += 2) {
;           float p0 = __builtin_amdgcn_exp2f(st[kb][i] - mn), p1 = __builtin_amdgcn_exp2f(st[kb][i + 1] - mn);
;           ps += p0 + p1;
;           unsigned pk = pack2bf(p0, p1);
;           pb[kb * 2 + (i >> 3)][i & 7] = (short)(pk & 0xffff);
;           pb[kb * 2 + (i >> 3)][(i & 7) + 1] = (short)(pk >> 16);
;         }
;       l = l * alpha + ps;
; #pragma unroll
;       for (int i = 0; i < 16; ++i) { ot[0][i] *= alpha; ot[1][i] *= alpha; }
;       const char* vb = cur + 64 * KP;
; #pragma unroll
;       for (int db = 0; db < 2; ++db)
; #pragma unroll
;         for (int s = 0; s < 4; ++s) {
;           const char* rp = vb + (db * 32 + n) * KP + (16 * s + 4 * hf) * 2;
;           typedef __attribute__((ext_vector_type(4))) short s16x4;
;           s16x4 lo = *(const s16x4*)rp, hi = *(const s16x4*)(rp + 16);
;           bf16x8 a;
;           a[0] = lo[0]; a[1] = lo[1]; a[2] = lo[2]; a[3] = lo[3]; a[4] = hi[0]; a[5] = hi[1]; a[6] = hi[2]; a[7] = hi[3];
.LBB0_389:
	s_or_b64 exec, exec, s[20:21]
	v_add3_u32 v232, s34, v134, v128
	v_lshrrev_b32_e32 v233, 2, v162
	v_and_b32_e32 v233, 8, v233
	v_add_u32_e32 v232, v232, v233
	v_add_u32_e32 v233, 0x2000, v232
	v_add_u32_e32 v234, 0x3000, v232
	ds_read_b128 v[200:203], v233 offset:1024
	ds_read_b128 v[204:207], v234 offset:1536
	ds_read_b128 v[208:211], v233 offset:1056
	ds_read_b128 v[212:215], v234 offset:1568
	ds_read_b128 v[216:219], v233 offset:1088
	ds_read_b128 v[220:223], v234 offset:1600
	ds_read_b128 v[224:227], v233 offset:1120
	ds_read_b128 v[228:231], v234 offset:1632
	v_max3_f32 v0, v64, s76, v65
	v_max3_f32 v0, v0, v66, v67
	v_max3_f32 v0, v0, v68, v69
	v_max3_f32 v0, v0, v70, v71
	v_max3_f32 v0, v0, v72, v73
	v_max3_f32 v0, v0, v74, v75
	v_max3_f32 v0, v0, v76, v77
	v_max3_f32 v0, v0, v78, v79
	v_max3_f32 v0, v0, v48, v49
	v_max3_f32 v0, v0, v50, v51
	v_max3_f32 v0, v0, v52, v53
	v_max3_f32 v0, v0, v54, v55
	v_max3_f32 v0, v0, v56, v57
	v_max3_f32 v0, v0, v58, v59
	v_max3_f32 v0, v0, v60, v61
	v_max3_f32 v0, v0, v62, v63
	v_mov_b32_e32 v2, v0
	s_nop 1
	v_permlane32_swap_b32_e32 v0, v2
	v_max_f32_e32 v0, v0, v2
	v_sub_f32_e32 v2, v0, v137
	v_cmp_lt_f32_e32 vcc, 0x41c00000, v2
	s_cbranch_vccz .Lat_noresc_a
	v_max_f32_e32 v138, v137, v0
	v_sub_f32_e32 v2, v137, v138
	v_exp_f32_e32 v2, v2
	v_mov_b32_e32 v137, v138
	s_nop 0
	v_mul_f32_e32 v136, v136, v2
	v_mul_f32_e32 v32, v32, v2
	v_mul_f32_e32 v33, v33, v2
	v_mul_f32_e32 v34, v34, v2
	v_mul_f32_e32 v35, v35, v2
	v_mul_f32_e32 v36, v36, v2
	v_mul_f32_e32 v37, v37, v2
	v_mul_f32_e32 v38, v38, v2
	v_mul_f32_e32 v39, v39, v2
	v_mul_f32_e32 v40, v40, v2
	v_mul_f32_e32 v41, v41, v2
	v_mul_f32_e32 v42, v42, v2
	v_mul_f32_e32 v43, v43, v2
	v_mul_f32_e32 v44, v44, v2
	v_mul_f32_e32 v45, v45, v2
	v_mul_f32_e32 v46, v46, v2
	v_mul_f32_e32 v47, v47, v2
	v_mul_f32_e32 v16, v16, v2
	v_mul_f32_e32 v17, v17, v2
	v_mul_f32_e32 v18, v18, v2
	v_mul_f32_e32 v19, v19, v2
	v_mul_f32_e32 v20, v20, v2
	v_mul_f32_e32 v21, v21, v2
	v_mul_f32_e32 v22, v22, v2
	v_mul_f32_e32 v23, v23, v2
	v_mul_f32_e32 v24, v24, v2
	v_mul_f32_e32 v25, v25, v2
	v_mul_f32_e32 v26, v26, v2
	v_mul_f32_e32 v27, v27, v2
	v_mul_f32_e32 v28, v28, v2
	v_mul_f32_e32 v29, v29, v2
	v_mul_f32_e32 v30, v30, v2
	v_mul_f32_e32 v31, v31, v2

; #define AT_ISSUE(T, KR, VR, CR) do { KR = *(const bf16x8*)(kg + (size_t)(T) * 64 * DIN); VR = *(const bf16x8*)(vg + (T) * 64); \
;     if (cth) CR = cc[(T) * 64 + tid]; } while (0)
; #define AT_WRITE(BUF, KR, VR, CR) do { char* _b = sm + (BUF) * BUFSZ; *(bf16x8*)(_b + soff) = KR; *(bf16x8*)(_b + 64 * KP + soff) = VR; \
;     if (cth) *(float*)(_b + 128 * KP + tid * 4) = -(CR) * LOG2E; } while (0)
; __device__ __forceinline__ void attn_item(const int WV, const Params& P, int bh, int qb) {
;     ...
;     if (kt + 2 < nkt) {
;       AT_WRITE((kt + 2) & 3, kA, vA, cA);
;       AT_WRITE((kt + 3) & 3, kB, vB, cB);
;       if (kt + 4 < nkt) { AT_ISSUE(kt + 4, kA, vA, cA); AT_ISSUE(kt + 5, kB, vB, cB); }
.LBB0_394:
	s_or_b64 exec, exec, s[12:13]
	s_add_i32 s20, s29, -1
	s_cmp_ge_u32 s20, s27
	s_cbranch_scc1 .LBB0_385
	s_and_b32 s21, s20, 2
	s_mulk_i32 s21, 0x4900
	v_add_u32_e32 v0, s21, v126
	s_waitcnt vmcnt(3)
	ds_write_b128 v0, v[96:99]
	s_waitcnt vmcnt(2)
	v_and_b32_e32 v175, 1, v162
	v_lshlrev_b32_e32 v175, 3, v175
	v_sub_u32_e32 v175, v0, v175
	v_add_u32_e32 v175, 0x2400, v175
	ds_write2_b64 v175, v[100:101], v[102:103] offset1:2
	s_and_saveexec_b64 s[12:13], s[4:5]
	s_xor_b64 s[12:13], exec, s[12:13]
	s_cbranch_execz .LBB0_398
	s_and_b32 s34, s29, 3
	s_mulk_i32 s34, 0x4900
	v_add_u32_e32 v0, s34, v126
	s_waitcnt vmcnt(1)
	ds_write_b128 v0, v[104:107]
	s_waitcnt vmcnt(0)
	v_and_b32_e32 v175, 1, v162
	v_lshlrev_b32_e32 v175, 3, v175
	v_sub_u32_e32 v175, v0, v175
	v_add_u32_e32 v175, 0x2400, v175
	ds_write2_b64 v175, v[108:109], v[110:111] offset1:2
	s_andn2_saveexec_b64 s[12:13], s[12:13]
	s_cbranch_execnz .LBB0_399

; #define AT_ISSUE(T, KR, VR, CR) do { KR = *(const bf16x8*)(kg + (size_t)(T) * 64 * DIN); VR = *(const bf16x8*)(vg + (T) * 64); \
;     if (cth) CR = cc[(T) * 64 + tid]; } while (0)
; #define AT_WRITE(BUF, KR, VR, CR) do { char* _b = sm + (BUF) * BUFSZ; *(bf16x8*)(_b + soff) = KR; *(bf16x8*)(_b + 64 * KP + soff) = VR; \
;     if (cth) *(float*)(_b + 128 * KP + tid * 4) = -(CR) * LOG2E; } while (0)
; __device__ __forceinline__ void attn_item(const int WV, const Params& P, int bh, int qb) {
;     ...
;     if (kt + 2 < nkt) {
;       AT_WRITE((kt + 2) & 3, kA, vA, cA);
;       AT_WRITE((kt + 3) & 3, kB, vB, cB);
;       if (kt + 4 < nkt) { AT_ISSUE(kt + 4, kA, vA, cA); AT_ISSUE(kt + 5, kB, vB, cB); }
.LBB0_399:
	v_add_u32_e32 v2, s21, v127
	s_and_b32 s21, s29, 3
	v_mul_f32_e32 v0, 0xbfb8aa3b, v119
	s_mulk_i32 s21, 0x4900
	ds_write_b32 v2, v0 offset:18432
	v_add_u32_e32 v0, s21, v126
	s_waitcnt vmcnt(1)
	ds_write_b128 v0, v[104:107]
	s_waitcnt vmcnt(0)
	v_and_b32_e32 v175, 1, v162
	v_lshlrev_b32_e32 v175, 3, v175
	v_sub_u32_e32 v175, v0, v175
	v_add_u32_e32 v175, 0x2400, v175
	ds_write2_b64 v175, v[108:109], v[110:111] offset1:2
	v_mul_f32_e32 v0, 0xbfb8aa3b, v117
	v_add_u32_e32 v2, s21, v127
	ds_write_b32 v2, v0 offset:18432
	s_or_b64 exec, exec, s[12:13]
	s_cmp_ge_u32 s33, s26
	s_cbranch_scc1 .LBB0_385
